# UQ GEMM RoPE epilogue: the 16 rope-table loads of a 32-column group issued up front with a constant counted vmcnt(14) per row (global ops) instead of 8 serialized load-wait-store round trips
# baseline (speedup 1.0000x reference)
; __device__ __forceinline__ unsigned cvt_pk_bf16(float lo, float hi) { unsigned r; asm volatile("v_cvt_pk_bf16_f32 %0, %1, %2" : "=v"(r) : "v"(lo), "v"(hi)); return r; }
;     __device__ __forceinline__ void operator()(const f32x4 (&acc)[2][2][4][2], const Unit& u, int wr, int wc, int fr_in, int fq_in) const {
;     ...
;         for (int bj = 0; bj < 2; ++bj) {
;             const int cg0 = u.pn * BM + bj * HALF + wc * 32;
;             if (cg0 >= 384) continue;
;             const bool isrope = ((cg0 >> 5) % 3) == 2;
; #pragma unroll
;             for (int ai = 0; ai < 2; ++ai)
; #pragma unroll
;                 for (int m = 0; m < 4; ++m) {
;                     const int r = row0 + ai * HALF + m * 16;
;                     f32x4 x1 = acc[ai][bj][m][0] * qs, x2 = acc[ai][bj][m][1] * qs;
;                     if (isrope) {
;                         const int s = r % LP;
;                         const f32x4 cs = *(const f32x4*)(rope + (size_t)s * 32 + 4 * fq), sn = *(const f32x4*)(rope + (size_t)s * 32 + 16 + 4 * fq);
;                         const f32x4 o1 = x1 * cs - x2 * sn, o2 = x2 * cs + x1 * sn; x1 = o1; x2 = o2;
;                     }
;                     bf16_t* p = U + (size_t)r * DIN + 2048 + cg0 + 4 * fq;
;                     u32x2 w1, w2; w1.x = cvt_pk_bf16(x1[0], x1[1]); w1.y = cvt_pk_bf16(x1[2], x1[3]); w2.x = cvt_pk_bf16(x2[0], x2[1]); w2.y = cvt_pk_bf16(x2[2], x2[3]);
;                     *(u32x2*)p = w1; *(u32x2*)(p + 16) = w2;
.LBB0_726:
	s_ashr_i32 s6, s36, 5
	s_mul_hi_i32 s7, s6, 0x55555556
	s_lshr_b32 s37, s7, 31
	s_add_i32 s7, s7, s37
	s_mul_i32 s7, s7, 3
	s_sub_i32 s6, s6, s7
	s_cmp_eq_u32 s6, 2
	s_cselect_b64 s[38:39], -1, 0
	s_cmp_lg_u32 s6, 2
	s_cbranch_scc1 .LBB0_728
	v_lshlrev_b32_e32 v238, 2, v75
	v_mov_b32_e32 v239, v1
	v_mov_b32_e32 v232, v74
	v_mul_hi_i32 v234, v232, s33
	v_lshrrev_b32_e32 v236, 31, v234
	v_ashrrev_i32_e32 v234, 12, v234
	v_add_u32_e32 v234, v234, v236
	v_mul_i32_i24_e32 v234, 0x2080, v234
	v_sub_u32_e32 v234, v232, v234
	v_ashrrev_i32_e32 v235, 31, v234
	v_lshlrev_b64 v[234:235], 7, v[234:235]
	v_lshl_add_u64 v[234:235], s[24:25], 0, v[234:235]
	v_lshl_add_u64 v[234:235], v[234:235], 0, v[238:239]
	global_load_dwordx4 v[160:163], v[234:235], off offset:64
	global_load_dwordx4 v[164:167], v[234:235], off
	v_add_u32_e32 v232, 16, v74
	v_mul_hi_i32 v234, v232, s33
	v_lshrrev_b32_e32 v236, 31, v234
	v_ashrrev_i32_e32 v234, 12, v234
	v_add_u32_e32 v234, v234, v236
	v_mul_i32_i24_e32 v234, 0x2080, v234
	v_sub_u32_e32 v234, v232, v234
	v_ashrrev_i32_e32 v235, 31, v234
	v_lshlrev_b64 v[234:235], 7, v[234:235]
	v_lshl_add_u64 v[234:235], s[24:25], 0, v[234:235]
	v_lshl_add_u64 v[234:235], v[234:235], 0, v[238:239]
	global_load_dwordx4 v[168:171], v[234:235], off offset:64
	global_load_dwordx4 v[172:175], v[234:235], off
	v_add_u32_e32 v232, 32, v74
	v_mul_hi_i32 v234, v232, s33
	v_lshrrev_b32_e32 v236, 31, v234
	v_ashrrev_i32_e32 v234, 12, v234
	v_add_u32_e32 v234, v234, v236
	v_mul_i32_i24_e32 v234, 0x2080, v234
	v_sub_u32_e32 v234, v232, v234
	v_ashrrev_i32_e32 v235, 31, v234
	v_lshlrev_b64 v[234:235], 7, v[234:235]
	v_lshl_add_u64 v[234:235], s[24:25], 0, v[234:235]
	v_lshl_add_u64 v[234:235], v[234:235], 0, v[238:239]
	global_load_dwordx4 v[176:179], v[234:235], off offset:64
	global_load_dwordx4 v[180:183], v[234:235], off
	v_add_u32_e32 v232, 48, v74
	v_mul_hi_i32 v234, v232, s33
	v_lshrrev_b32_e32 v236, 31, v234
	v_ashrrev_i32_e32 v234, 12, v234
	v_add_u32_e32 v234, v234, v236
	v_mul_i32_i24_e32 v234, 0x2080, v234
	v_sub_u32_e32 v234, v232, v234
	v_ashrrev_i32_e32 v235, 31, v234
	v_lshlrev_b64 v[234:235], 7, v[234:235]
	v_lshl_add_u64 v[234:235], s[24:25], 0, v[234:235]
	v_lshl_add_u64 v[234:235], v[234:235], 0, v[238:239]
	global_load_dwordx4 v[184:187], v[234:235], off offset:64
	global_load_dwordx4 v[188:191], v[234:235], off
	v_add_u32_e32 v232, 0x80, v74
	v_mul_hi_i32 v234, v232, s33
	v_lshrrev_b32_e32 v236, 31, v234
	v_ashrrev_i32_e32 v234, 12, v234
	v_add_u32_e32 v234, v234, v236
	v_mul_i32_i24_e32 v234, 0x2080, v234
	v_sub_u32_e32 v234, v232, v234
	v_ashrrev_i32_e32 v235, 31, v234
	v_lshlrev_b64 v[234:235], 7, v[234:235]
	v_lshl_add_u64 v[234:235], s[24:25], 0, v[234:235]
	v_lshl_add_u64 v[234:235], v[234:235], 0, v[238:239]
	global_load_dwordx4 v[192:195], v[234:235], off offset:64
	global_load_dwordx4 v[196:199], v[234:235], off
	v_add_u32_e32 v232, 0x90, v74
	v_mul_hi_i32 v234, v232, s33
	v_lshrrev_b32_e32 v236, 31, v234
	v_ashrrev_i32_e32 v234, 12, v234
	v_add_u32_e32 v234, v234, v236
	v_mul_i32_i24_e32 v234, 0x2080, v234
	v_sub_u32_e32 v234, v232, v234
	v_ashrrev_i32_e32 v235, 31, v234
	v_lshlrev_b64 v[234:235], 7, v[234:235]
	v_lshl_add_u64 v[234:235], s[24:25], 0, v[234:235]
	v_lshl_add_u64 v[234:235], v[234:235], 0, v[238:239]
	global_load_dwordx4 v[200:203], v[234:235], off offset:64
	global_load_dwordx4 v[204:207], v[234:235], off
	v_add_u32_e32 v232, 0xa0, v74
	v_mul_hi_i32 v234, v232, s33
	v_lshrrev_b32_e32 v236, 31, v234
	v_ashrrev_i32_e32 v234, 12, v234
	v_add_u32_e32 v234, v234, v236
	v_mul_i32_i24_e32 v234, 0x2080, v234
	v_sub_u32_e32 v234, v232, v234
	v_ashrrev_i32_e32 v235, 31, v234
	v_lshlrev_b64 v[234:235], 7, v[234:235]
	v_lshl_add_u64 v[234:235], s[24:25], 0, v[234:235]
	v_lshl_add_u64 v[234:235], v[234:235], 0, v[238:239]
	global_load_dwordx4 v[208:211], v[234:235], off offset:64
	global_load_dwordx4 v[220:223], v[234:235], off
	v_add_u32_e32 v232, 0xb0, v74
	v_mul_hi_i32 v234, v232, s33
	v_lshrrev_b32_e32 v236, 31, v234
	v_ashrrev_i32_e32 v234, 12, v234
	v_add_u32_e32 v234, v234, v236
	v_mul_i32_i24_e32 v234, 0x2080, v234
	v_sub_u32_e32 v234, v232, v234
	v_ashrrev_i32_e32 v235, 31, v234
	v_lshlrev_b64 v[234:235], 7, v[234:235]
	v_lshl_add_u64 v[234:235], s[24:25], 0, v[234:235]
	v_lshl_add_u64 v[234:235], v[234:235], 0, v[238:239]
	global_load_dwordx4 v[224:227], v[234:235], off offset:64
	global_load_dwordx4 v[228:231], v[234:235], off
	s_waitcnt vmcnt(14)
	v_pk_mul_f32 v[80:81], v[144:145], v[162:163]
	v_pk_mul_f32 v[94:95], v[142:143], v[160:161]
	v_pk_mul_f32 v[162:163], v[148:149], v[162:163]
	v_pk_mul_f32 v[160:161], v[146:147], v[160:161]
	v_pk_fma_f32 v[148:149], v[148:149], v[166:167], v[80:81] neg_lo:[0,0,1] neg_hi:[0,0,1]
	v_pk_fma_f32 v[146:147], v[146:147], v[164:165], v[94:95] neg_lo:[0,0,1] neg_hi:[0,0,1]
	v_pk_fma_f32 v[144:145], v[144:145], v[166:167], v[162:163]
	v_pk_fma_f32 v[142:143], v[142:143], v[164:165], v[160:161]
.LBB0_728:
	v_mov_b64_e32 v[76:77], s[16:17]
	s_ashr_i32 s37, s36, 31
	v_mad_i64_i32 v[76:77], s[6:7], v74, s45, v[76:77]
	v_lshl_add_u64 v[76:77], s[36:37], 1, v[76:77]
	v_lshlrev_b32_e32 v0, 1, v75
	v_lshl_add_u64 v[76:77], v[76:77], 0, v[0:1]
	v_lshl_add_u64 v[78:79], v[76:77], 0, s[84:85]
	v_add_co_u32_e32 v76, vcc, 0x1000, v76
	v_cvt_pk_bf16_f32 v80, v146, v147
	v_cvt_pk_bf16_f32 v81, v148, v149
	v_cvt_pk_bf16_f32 v90, v142, v143
	v_cvt_pk_bf16_f32 v91, v144, v145
	s_nop 1
	v_addc_co_u32_e32 v77, vcc, 0, v77, vcc
	global_store_dwordx2 v[76:77], v[80:81], off
	global_store_dwordx2 v[78:79], v[90:91], off offset:32
	v_cndmask_b32_e64 v76, 0, 1, s[38:39]
	v_cmp_ne_u32_e64 s[6:7], 1, v76
	s_andn2_b64 vcc, exec, s[38:39]
	v_or_b32_e32 v76, 16, v74
	s_cbranch_vccnz .LBB0_730
	s_waitcnt vmcnt(14)
	v_pk_mul_f32 v[94:95], v[136:137], v[170:171]
	v_pk_mul_f32 v[96:97], v[134:135], v[168:169]
	v_pk_mul_f32 v[170:171], v[140:141], v[170:171]
	v_pk_mul_f32 v[168:169], v[138:139], v[168:169]
	v_pk_fma_f32 v[140:141], v[140:141], v[174:175], v[94:95] neg_lo:[0,0,1] neg_hi:[0,0,1]
	v_pk_fma_f32 v[138:139], v[138:139], v[172:173], v[96:97] neg_lo:[0,0,1] neg_hi:[0,0,1]
	v_pk_fma_f32 v[136:137], v[136:137], v[174:175], v[170:171]
	v_pk_fma_f32 v[134:135], v[134:135], v[172:173], v[168:169]
; __device__ __forceinline__ unsigned cvt_pk_bf16(float lo, float hi) { unsigned r; asm volatile("v_cvt_pk_bf16_f32 %0, %1, %2" : "=v"(r) : "v"(lo), "v"(hi)); return r; }
;     __device__ __forceinline__ void operator()(const f32x4 (&acc)[2][2][4][2], const Unit& u, int wr, int wc, int fr_in, int fq_in) const {
;     ...
;             for (int ai = 0; ai < 2; ++ai)
; #pragma unroll
;                 for (int m = 0; m < 4; ++m) {
;                     const int r = row0 + ai * HALF + m * 16;
;                     f32x4 x1 = acc[ai][bj][m][0] * qs, x2 = acc[ai][bj][m][1] * qs;
;                     if (isrope) {
;                         const int s = r % LP;
;                         const f32x4 cs = *(const f32x4*)(rope + (size_t)s * 32 + 4 * fq), sn = *(const f32x4*)(rope + (size_t)s * 32 + 16 + 4 * fq);
;                         const f32x4 o1 = x1 * cs - x2 * sn, o2 = x2 * cs + x1 * sn; x1 = o1; x2 = o2;
;                     }
;                     bf16_t* p = U + (size_t)r * DIN + 2048 + cg0 + 4 * fq;
;                     u32x2 w1, w2; w1.x = cvt_pk_bf16(x1[0], x1[1]); w1.y = cvt_pk_bf16(x1[2], x1[3]); w2.x = cvt_pk_bf16(x2[0], x2[1]); w2.y = cvt_pk_bf16(x2[2], x2[3]);
;                     *(u32x2*)p = w1; *(u32x2*)(p + 16) = w2;
.LBB0_730:
	v_mov_b64_e32 v[78:79], s[16:17]
	v_mad_i64_i32 v[76:77], s[38:39], v76, s45, v[78:79]
	v_lshl_add_u64 v[76:77], s[36:37], 1, v[76:77]
	v_lshl_add_u64 v[76:77], v[76:77], 0, v[0:1]
	v_lshl_add_u64 v[78:79], v[76:77], 0, s[84:85]
	v_add_co_u32_e32 v76, vcc, 0x1000, v76
	v_cvt_pk_bf16_f32 v80, v138, v139
	v_cvt_pk_bf16_f32 v81, v140, v141
	v_cvt_pk_bf16_f32 v90, v134, v135
	v_cvt_pk_bf16_f32 v91, v136, v137
	s_nop 1
	v_addc_co_u32_e32 v77, vcc, 0, v77, vcc
	global_store_dwordx2 v[76:77], v[80:81], off
	global_store_dwordx2 v[78:79], v[90:91], off offset:32
	s_and_b64 vcc, exec, s[6:7]
	v_or_b32_e32 v76, 32, v74
	s_cbranch_vccnz .LBB0_732
	s_waitcnt vmcnt(14)
	v_pk_mul_f32 v[94:95], v[128:129], v[178:179]
	v_pk_mul_f32 v[96:97], v[126:127], v[176:177]
	v_pk_mul_f32 v[178:179], v[132:133], v[178:179]
	v_pk_mul_f32 v[176:177], v[130:131], v[176:177]
	v_pk_fma_f32 v[132:133], v[132:133], v[182:183], v[94:95] neg_lo:[0,0,1] neg_hi:[0,0,1]
	v_pk_fma_f32 v[130:131], v[130:131], v[180:181], v[96:97] neg_lo:[0,0,1] neg_hi:[0,0,1]
	v_pk_fma_f32 v[128:129], v[128:129], v[182:183], v[178:179]
	v_pk_fma_f32 v[126:127], v[126:127], v[180:181], v[176:177]
.LBB0_732:
	v_mov_b64_e32 v[78:79], s[16:17]
	v_mad_i64_i32 v[76:77], s[38:39], v76, s45, v[78:79]
	v_lshl_add_u64 v[76:77], s[36:37], 1, v[76:77]
	v_lshl_add_u64 v[76:77], v[76:77], 0, v[0:1]
	v_lshl_add_u64 v[78:79], v[76:77], 0, s[84:85]
	v_add_co_u32_e32 v76, vcc, 0x1000, v76
	v_cvt_pk_bf16_f32 v80, v130, v131
	v_cvt_pk_bf16_f32 v81, v132, v133
	v_cvt_pk_bf16_f32 v90, v126, v127
	v_cvt_pk_bf16_f32 v91, v128, v129
	s_nop 1
	v_addc_co_u32_e32 v77, vcc, 0, v77, vcc
	global_store_dwordx2 v[76:77], v[80:81], off
	global_store_dwordx2 v[78:79], v[90:91], off offset:32
	s_and_b64 vcc, exec, s[6:7]
	v_or_b32_e32 v76, 48, v74
	s_cbranch_vccnz .LBB0_734
	s_waitcnt vmcnt(14)
	v_pk_mul_f32 v[94:95], v[120:121], v[186:187]
	v_pk_mul_f32 v[96:97], v[118:119], v[184:185]
	v_pk_mul_f32 v[186:187], v[124:125], v[186:187]
	v_pk_mul_f32 v[184:185], v[122:123], v[184:185]
	v_pk_fma_f32 v[124:125], v[124:125], v[190:191], v[94:95] neg_lo:[0,0,1] neg_hi:[0,0,1]
	v_pk_fma_f32 v[122:123], v[122:123], v[188:189], v[96:97] neg_lo:[0,0,1] neg_hi:[0,0,1]
	v_pk_fma_f32 v[120:121], v[120:121], v[190:191], v[186:187]
	v_pk_fma_f32 v[118:119], v[118:119], v[188:189], v[184:185]
.LBB0_734:
	v_mov_b64_e32 v[78:79], s[16:17]
	v_mad_i64_i32 v[76:77], s[38:39], v76, s45, v[78:79]
	v_lshl_add_u64 v[76:77], s[36:37], 1, v[76:77]
	v_lshl_add_u64 v[76:77], v[76:77], 0, v[0:1]
	v_lshl_add_u64 v[78:79], v[76:77], 0, s[84:85]
	v_add_co_u32_e32 v76, vcc, 0x1000, v76
	v_cvt_pk_bf16_f32 v80, v122, v123
	v_cvt_pk_bf16_f32 v81, v124, v125
	v_cvt_pk_bf16_f32 v90, v118, v119
	v_cvt_pk_bf16_f32 v91, v120, v121
	s_nop 1
	v_addc_co_u32_e32 v77, vcc, 0, v77, vcc
	global_store_dwordx2 v[76:77], v[80:81], off
	global_store_dwordx2 v[78:79], v[90:91], off offset:32
	s_and_b64 vcc, exec, s[6:7]
	v_add_u32_e32 v76, 0x80, v74
	s_cbranch_vccnz .LBB0_736
	s_waitcnt vmcnt(14)
	v_pk_mul_f32 v[94:95], v[112:113], v[194:195]
	v_pk_mul_f32 v[96:97], v[110:111], v[192:193]
	v_pk_mul_f32 v[194:195], v[116:117], v[194:195]
	v_pk_mul_f32 v[192:193], v[114:115], v[192:193]
	v_pk_fma_f32 v[116:117], v[116:117], v[198:199], v[94:95] neg_lo:[0,0,1] neg_hi:[0,0,1]
	v_pk_fma_f32 v[114:115], v[114:115], v[196:197], v[96:97] neg_lo:[0,0,1] neg_hi:[0,0,1]
	v_pk_fma_f32 v[112:113], v[112:113], v[198:199], v[194:195]
	v_pk_fma_f32 v[110:111], v[110:111], v[196:197], v[192:193]
.LBB0_736:
	v_mov_b64_e32 v[78:79], s[16:17]
	v_mad_i64_i32 v[76:77], s[38:39], v76, s45, v[78:79]
	v_lshl_add_u64 v[76:77], s[36:37], 1, v[76:77]
	v_lshl_add_u64 v[76:77], v[76:77], 0, v[0:1]
	v_lshl_add_u64 v[78:79], v[76:77], 0, s[84:85]
	v_add_co_u32_e32 v76, vcc, 0x1000, v76
	v_cvt_pk_bf16_f32 v80, v114, v115
	v_cvt_pk_bf16_f32 v81, v116, v117
	v_cvt_pk_bf16_f32 v90, v110, v111
	v_cvt_pk_bf16_f32 v91, v112, v113
	s_nop 1
	v_addc_co_u32_e32 v77, vcc, 0, v77, vcc
	global_store_dwordx2 v[76:77], v[80:81], off
	global_store_dwordx2 v[78:79], v[90:91], off offset:32
	s_and_b64 vcc, exec, s[6:7]
	v_add_u32_e32 v76, 0x90, v74
	s_cbranch_vccnz .LBB0_738
	s_waitcnt vmcnt(14)
	v_pk_mul_f32 v[94:95], v[104:105], v[202:203]
	v_pk_mul_f32 v[96:97], v[102:103], v[200:201]
	v_pk_mul_f32 v[202:203], v[108:109], v[202:203]
	v_pk_mul_f32 v[200:201], v[106:107], v[200:201]
	v_pk_fma_f32 v[108:109], v[108:109], v[206:207], v[94:95] neg_lo:[0,0,1] neg_hi:[0,0,1]
	v_pk_fma_f32 v[106:107], v[106:107], v[204:205], v[96:97] neg_lo:[0,0,1] neg_hi:[0,0,1]
	v_pk_fma_f32 v[104:105], v[104:105], v[206:207], v[202:203]
	v_pk_fma_f32 v[102:103], v[102:103], v[204:205], v[200:201]
.LBB0_738:
	v_mov_b64_e32 v[78:79], s[16:17]
	v_mad_i64_i32 v[76:77], s[38:39], v76, s45, v[78:79]
	v_lshl_add_u64 v[76:77], s[36:37], 1, v[76:77]
	v_lshl_add_u64 v[76:77], v[76:77], 0, v[0:1]
	v_lshl_add_u64 v[78:79], v[76:77], 0, s[84:85]
	v_add_co_u32_e32 v76, vcc, 0x1000, v76
	v_cvt_pk_bf16_f32 v80, v106, v107
	v_cvt_pk_bf16_f32 v81, v108, v109
	v_cvt_pk_bf16_f32 v90, v102, v103
	v_cvt_pk_bf16_f32 v91, v104, v105
	s_nop 1
	v_addc_co_u32_e32 v77, vcc, 0, v77, vcc
	global_store_dwordx2 v[76:77], v[80:81], off
	global_store_dwordx2 v[78:79], v[90:91], off offset:32
	s_and_b64 vcc, exec, s[6:7]
	v_add_u32_e32 v76, 0xa0, v74
	s_cbranch_vccnz .LBB0_740
	s_waitcnt vmcnt(14)
	v_pk_mul_f32 v[94:95], v[84:85], v[210:211]
	v_pk_mul_f32 v[96:97], v[82:83], v[208:209]
	v_pk_mul_f32 v[210:211], v[88:89], v[210:211]
	v_pk_mul_f32 v[208:209], v[86:87], v[208:209]
	v_pk_fma_f32 v[88:89], v[88:89], v[222:223], v[94:95] neg_lo:[0,0,1] neg_hi:[0,0,1]
	v_pk_fma_f32 v[86:87], v[86:87], v[220:221], v[96:97] neg_lo:[0,0,1] neg_hi:[0,0,1]
	v_pk_fma_f32 v[84:85], v[84:85], v[222:223], v[210:211]
	v_pk_fma_f32 v[82:83], v[82:83], v[220:221], v[208:209]
; __device__ __forceinline__ unsigned cvt_pk_bf16(float lo, float hi) { unsigned r; asm volatile("v_cvt_pk_bf16_f32 %0, %1, %2" : "=v"(r) : "v"(lo), "v"(hi)); return r; }
;     __device__ __forceinline__ void operator()(const f32x4 (&acc)[2][2][4][2], const Unit& u, int wr, int wc, int fr_in, int fq_in) const {
;     ...
;         for (int bj = 0; bj < 2; ++bj) {
;             const int cg0 = u.pn * BM + bj * HALF + wc * 32;
;             if (cg0 >= 384) continue;
;             const bool isrope = ((cg0 >> 5) % 3) == 2;
; #pragma unroll
;             for (int ai = 0; ai < 2; ++ai)
; #pragma unroll
;                 for (int m = 0; m < 4; ++m) {
;                     const int r = row0 + ai * HALF + m * 16;
;                     f32x4 x1 = acc[ai][bj][m][0] * qs, x2 = acc[ai][bj][m][1] * qs;
;                     if (isrope) {
;                         const int s = r % LP;
;                         const f32x4 cs = *(const f32x4*)(rope + (size_t)s * 32 + 4 * fq), sn = *(const f32x4*)(rope + (size_t)s * 32 + 16 + 4 * fq);
;                         const f32x4 o1 = x1 * cs - x2 * sn, o2 = x2 * cs + x1 * sn; x1 = o1; x2 = o2;
;                     }
;                     bf16_t* p = U + (size_t)r * DIN + 2048 + cg0 + 4 * fq;
;                     u32x2 w1, w2; w1.x = cvt_pk_bf16(x1[0], x1[1]); w1.y = cvt_pk_bf16(x1[2], x1[3]); w2.x = cvt_pk_bf16(x2[0], x2[1]); w2.y = cvt_pk_bf16(x2[2], x2[3]);
;                     *(u32x2*)p = w1; *(u32x2*)(p + 16) = w2;
.LBB0_740:
	v_mov_b64_e32 v[78:79], s[16:17]
	v_mad_i64_i32 v[76:77], s[38:39], v76, s45, v[78:79]
	v_lshl_add_u64 v[76:77], s[36:37], 1, v[76:77]
	v_lshl_add_u64 v[76:77], v[76:77], 0, v[0:1]
	v_lshl_add_u64 v[78:79], v[76:77], 0, s[84:85]
	v_add_co_u32_e32 v76, vcc, 0x1000, v76
	v_cvt_pk_bf16_f32 v80, v86, v87
	v_cvt_pk_bf16_f32 v81, v88, v89
	v_cvt_pk_bf16_f32 v82, v82, v83
	v_cvt_pk_bf16_f32 v83, v84, v85
	s_nop 1
	v_addc_co_u32_e32 v77, vcc, 0, v77, vcc
	global_store_dwordx2 v[76:77], v[80:81], off
	global_store_dwordx2 v[78:79], v[82:83], off offset:32
	s_and_b64 vcc, exec, s[6:7]
	v_add_u32_e32 v76, 0xb0, v74
	s_cbranch_vccnz .LBB0_742
	s_waitcnt vmcnt(14)
	v_pk_mul_f32 v[86:87], v[68:69], v[226:227]
	v_pk_mul_f32 v[88:89], v[66:67], v[224:225]
	v_pk_mul_f32 v[226:227], v[72:73], v[226:227]
	v_pk_mul_f32 v[224:225], v[70:71], v[224:225]
	v_pk_fma_f32 v[72:73], v[72:73], v[230:231], v[86:87] neg_lo:[0,0,1] neg_hi:[0,0,1]
	v_pk_fma_f32 v[70:71], v[70:71], v[228:229], v[88:89] neg_lo:[0,0,1] neg_hi:[0,0,1]
	v_pk_fma_f32 v[68:69], v[68:69], v[230:231], v[226:227]
	v_pk_fma_f32 v[66:67], v[66:67], v[228:229], v[224:225]
.LBB0_742:
	v_mov_b64_e32 v[78:79], s[16:17]
	v_mad_i64_i32 v[76:77], s[6:7], v76, s45, v[78:79]
	v_lshl_add_u64 v[76:77], s[36:37], 1, v[76:77]
	v_lshl_add_u64 v[76:77], v[76:77], 0, v[0:1]
	v_cvt_pk_bf16_f32 v70, v70, v71
	v_cvt_pk_bf16_f32 v71, v72, v73
	v_cvt_pk_bf16_f32 v66, v66, v67
	v_cvt_pk_bf16_f32 v67, v68, v69
	v_add_co_u32_e32 v68, vcc, 0x1000, v76
	v_lshl_add_u64 v[78:79], v[76:77], 0, s[84:85]
	s_nop 0
	v_addc_co_u32_e32 v69, vcc, 0, v77, vcc
	global_store_dwordx2 v[68:69], v[70:71], off
	global_store_dwordx2 v[78:79], v[66:67], off offset:32
	s_bitset1_b32 s36, 7
	s_cmpk_gt_i32 s36, 0x17f
	s_cbranch_scc1 .LBB0_725
.LBB0_743:
	s_ashr_i32 s6, s36, 5
	s_mul_hi_i32 s7, s6, 0x55555556
	s_lshr_b32 s37, s7, 31
	s_add_i32 s7, s7, s37
	s_mul_i32 s7, s7, 3
	s_sub_i32 s6, s6, s7
	s_cmp_eq_u32 s6, 2
	s_cselect_b64 s[38:39], -1, 0
	s_cmp_lg_u32 s6, 2
	v_lshlrev_b32_e32 v66, 2, v75
	s_cbranch_scc1 .LBB0_745
	v_lshlrev_b32_e32 v238, 2, v75
	v_mov_b32_e32 v239, v1
	v_mov_b32_e32 v232, v74
	v_mul_hi_i32 v234, v232, s33
	v_lshrrev_b32_e32 v236, 31, v234
	v_ashrrev_i32_e32 v234, 12, v234
	v_add_u32_e32 v234, v234, v236
	v_mul_i32_i24_e32 v234, 0x2080, v234
	v_sub_u32_e32 v234, v232, v234
	v_ashrrev_i32_e32 v235, 31, v234
	v_lshlrev_b64 v[234:235], 7, v[234:235]
	v_lshl_add_u64 v[234:235], s[24:25], 0, v[234:235]
	v_lshl_add_u64 v[234:235], v[234:235], 0, v[238:239]
	global_load_dwordx4 v[160:163], v[234:235], off offset:64
	global_load_dwordx4 v[164:167], v[234:235], off
	v_add_u32_e32 v232, 16, v74
	v_mul_hi_i32 v234, v232, s33
	v_lshrrev_b32_e32 v236, 31, v234
	v_ashrrev_i32_e32 v234, 12, v234
	v_add_u32_e32 v234, v234, v236
	v_mul_i32_i24_e32 v234, 0x2080, v234
	v_sub_u32_e32 v234, v232, v234
	v_ashrrev_i32_e32 v235, 31, v234
	v_lshlrev_b64 v[234:235], 7, v[234:235]
	v_lshl_add_u64 v[234:235], s[24:25], 0, v[234:235]
	v_lshl_add_u64 v[234:235], v[234:235], 0, v[238:239]
	global_load_dwordx4 v[168:171], v[234:235], off offset:64
	global_load_dwordx4 v[172:175], v[234:235], off
	v_add_u32_e32 v232, 32, v74
	v_mul_hi_i32 v234, v232, s33
	v_lshrrev_b32_e32 v236, 31, v234
	v_ashrrev_i32_e32 v234, 12, v234
	v_add_u32_e32 v234, v234, v236
	v_mul_i32_i24_e32 v234, 0x2080, v234
	v_sub_u32_e32 v234, v232, v234
	v_ashrrev_i32_e32 v235, 31, v234
	v_lshlrev_b64 v[234:235], 7, v[234:235]
	v_lshl_add_u64 v[234:235], s[24:25], 0, v[234:235]
	v_lshl_add_u64 v[234:235], v[234:235], 0, v[238:239]
	global_load_dwordx4 v[176:179], v[234:235], off offset:64
	global_load_dwordx4 v[180:183], v[234:235], off
	v_add_u32_e32 v232, 48, v74
	v_mul_hi_i32 v234, v232, s33
	v_lshrrev_b32_e32 v236, 31, v234
	v_ashrrev_i32_e32 v234, 12, v234
	v_add_u32_e32 v234, v234, v236
	v_mul_i32_i24_e32 v234, 0x2080, v234
	v_sub_u32_e32 v234, v232, v234
	v_ashrrev_i32_e32 v235, 31, v234
	v_lshlrev_b64 v[234:235], 7, v[234:235]
	v_lshl_add_u64 v[234:235], s[24:25], 0, v[234:235]
	v_lshl_add_u64 v[234:235], v[234:235], 0, v[238:239]
	global_load_dwordx4 v[184:187], v[234:235], off offset:64
	global_load_dwordx4 v[188:191], v[234:235], off
	v_add_u32_e32 v232, 0x80, v74
	v_mul_hi_i32 v234, v232, s33
	v_lshrrev_b32_e32 v236, 31, v234
	v_ashrrev_i32_e32 v234, 12, v234
	v_add_u32_e32 v234, v234, v236
	v_mul_i32_i24_e32 v234, 0x2080, v234
	v_sub_u32_e32 v234, v232, v234
	v_ashrrev_i32_e32 v235, 31, v234
	v_lshlrev_b64 v[234:235], 7, v[234:235]
	v_lshl_add_u64 v[234:235], s[24:25], 0, v[234:235]
	v_lshl_add_u64 v[234:235], v[234:235], 0, v[238:239]
	global_load_dwordx4 v[192:195], v[234:235], off offset:64
	global_load_dwordx4 v[196:199], v[234:235], off
	v_add_u32_e32 v232, 0x90, v74
	v_mul_hi_i32 v234, v232, s33
	v_lshrrev_b32_e32 v236, 31, v234
	v_ashrrev_i32_e32 v234, 12, v234
	v_add_u32_e32 v234, v234, v236
	v_mul_i32_i24_e32 v234, 0x2080, v234
	v_sub_u32_e32 v234, v232, v234
	v_ashrrev_i32_e32 v235, 31, v234
	v_lshlrev_b64 v[234:235], 7, v[234:235]
	v_lshl_add_u64 v[234:235], s[24:25], 0, v[234:235]
	v_lshl_add_u64 v[234:235], v[234:235], 0, v[238:239]
	global_load_dwordx4 v[200:203], v[234:235], off offset:64
	global_load_dwordx4 v[204:207], v[234:235], off
	v_add_u32_e32 v232, 0xa0, v74
	v_mul_hi_i32 v234, v232, s33
	v_lshrrev_b32_e32 v236, 31, v234
	v_ashrrev_i32_e32 v234, 12, v234
	v_add_u32_e32 v234, v234, v236
	v_mul_i32_i24_e32 v234, 0x2080, v234
	v_sub_u32_e32 v234, v232, v234
	v_ashrrev_i32_e32 v235, 31, v234
	v_lshlrev_b64 v[234:235], 7, v[234:235]
	v_lshl_add_u64 v[234:235], s[24:25], 0, v[234:235]
	v_lshl_add_u64 v[234:235], v[234:235], 0, v[238:239]
	global_load_dwordx4 v[208:211], v[234:235], off offset:64
	global_load_dwordx4 v[220:223], v[234:235], off
	v_add_u32_e32 v232, 0xb0, v74
	v_mul_hi_i32 v234, v232, s33
	v_lshrrev_b32_e32 v236, 31, v234
	v_ashrrev_i32_e32 v234, 12, v234
	v_add_u32_e32 v234, v234, v236
	v_mul_i32_i24_e32 v234, 0x2080, v234
	v_sub_u32_e32 v234, v232, v234
	v_ashrrev_i32_e32 v235, 31, v234
	v_lshlrev_b64 v[234:235], 7, v[234:235]
	v_lshl_add_u64 v[234:235], s[24:25], 0, v[234:235]
	v_lshl_add_u64 v[234:235], v[234:235], 0, v[238:239]
	global_load_dwordx4 v[224:227], v[234:235], off offset:64
	global_load_dwordx4 v[228:231], v[234:235], off
	s_waitcnt vmcnt(14)
	v_pk_mul_f32 v[72:73], v[60:61], v[162:163]
	v_pk_mul_f32 v[80:81], v[58:59], v[160:161]
	v_pk_mul_f32 v[162:163], v[64:65], v[162:163]
	v_pk_mul_f32 v[160:161], v[62:63], v[160:161]
	v_pk_fma_f32 v[64:65], v[64:65], v[166:167], v[72:73] neg_lo:[0,0,1] neg_hi:[0,0,1]
	v_pk_fma_f32 v[62:63], v[62:63], v[164:165], v[80:81] neg_lo:[0,0,1] neg_hi:[0,0,1]
	v_pk_fma_f32 v[60:61], v[60:61], v[166:167], v[162:163]
	v_pk_fma_f32 v[58:59], v[58:59], v[164:165], v[160:161]
; __device__ __forceinline__ unsigned cvt_pk_bf16(float lo, float hi) { unsigned r; asm volatile("v_cvt_pk_bf16_f32 %0, %1, %2" : "=v"(r) : "v"(lo), "v"(hi)); return r; }
;     __device__ __forceinline__ void operator()(const f32x4 (&acc)[2][2][4][2], const Unit& u, int wr, int wc, int fr_in, int fq_in) const {
;     ...
;             for (int ai = 0; ai < 2; ++ai)
; #pragma unroll
;                 for (int m = 0; m < 4; ++m) {
;                     const int r = row0 + ai * HALF + m * 16;
;                     f32x4 x1 = acc[ai][bj][m][0] * qs, x2 = acc[ai][bj][m][1] * qs;
;                     if (isrope) {
;                         const int s = r % LP;
;                         const f32x4 cs = *(const f32x4*)(rope + (size_t)s * 32 + 4 * fq), sn = *(const f32x4*)(rope + (size_t)s * 32 + 16 + 4 * fq);
;                         const f32x4 o1 = x1 * cs - x2 * sn, o2 = x2 * cs + x1 * sn; x1 = o1; x2 = o2;
;                     }
;                     bf16_t* p = U + (size_t)r * DIN + 2048 + cg0 + 4 * fq;
;                     u32x2 w1, w2; w1.x = cvt_pk_bf16(x1[0], x1[1]); w1.y = cvt_pk_bf16(x1[2], x1[3]); w2.x = cvt_pk_bf16(x2[0], x2[1]); w2.y = cvt_pk_bf16(x2[2], x2[3]);
;                     *(u32x2*)p = w1; *(u32x2*)(p + 16) = w2;
.LBB0_745:
	v_mov_b64_e32 v[68:69], s[16:17]
	v_mad_i64_i32 v[68:69], s[6:7], v74, s45, v[68:69]
	v_lshlrev_b32_e32 v0, 1, v75
	s_ashr_i32 s37, s36, 31
	v_lshl_add_u64 v[68:69], v[68:69], 0, v[0:1]
	v_lshl_add_u64 v[68:69], s[36:37], 1, v[68:69]
	v_cvt_pk_bf16_f32 v62, v62, v63
	v_cvt_pk_bf16_f32 v63, v64, v65
	v_cvt_pk_bf16_f32 v58, v58, v59
	v_cvt_pk_bf16_f32 v59, v60, v61
	v_add_co_u32_e32 v60, vcc, 0x1000, v68
	v_lshl_add_u64 v[70:71], v[68:69], 0, s[84:85]
	s_nop 0
	v_addc_co_u32_e32 v61, vcc, 0, v69, vcc
	global_store_dwordx2 v[60:61], v[62:63], off
	global_store_dwordx2 v[70:71], v[58:59], off offset:32
	v_cndmask_b32_e64 v58, 0, 1, s[38:39]
	v_cmp_ne_u32_e64 s[6:7], 1, v58
	s_andn2_b64 vcc, exec, s[38:39]
	v_or_b32_e32 v58, 16, v74
	s_cbranch_vccnz .LBB0_747
	s_waitcnt vmcnt(14)
	v_pk_mul_f32 v[64:65], v[52:53], v[170:171]
	v_pk_mul_f32 v[72:73], v[50:51], v[168:169]
	v_pk_mul_f32 v[170:171], v[56:57], v[170:171]
	v_pk_mul_f32 v[168:169], v[54:55], v[168:169]
	v_pk_fma_f32 v[56:57], v[56:57], v[174:175], v[64:65] neg_lo:[0,0,1] neg_hi:[0,0,1]
	v_pk_fma_f32 v[54:55], v[54:55], v[172:173], v[72:73] neg_lo:[0,0,1] neg_hi:[0,0,1]
	v_pk_fma_f32 v[52:53], v[52:53], v[174:175], v[170:171]
	v_pk_fma_f32 v[50:51], v[50:51], v[172:173], v[168:169]
.LBB0_747:
	v_mov_b64_e32 v[60:61], s[16:17]
	v_mad_i64_i32 v[58:59], s[38:39], v58, s45, v[60:61]
	v_lshl_add_u64 v[58:59], v[58:59], 0, v[0:1]
	v_lshl_add_u64 v[58:59], s[36:37], 1, v[58:59]
	v_cvt_pk_bf16_f32 v54, v54, v55
	v_cvt_pk_bf16_f32 v55, v56, v57
	v_cvt_pk_bf16_f32 v50, v50, v51
	v_cvt_pk_bf16_f32 v51, v52, v53
	v_add_co_u32_e32 v52, vcc, 0x1000, v58
	v_lshl_add_u64 v[60:61], v[58:59], 0, s[84:85]
	s_nop 0
	v_addc_co_u32_e32 v53, vcc, 0, v59, vcc
	global_store_dwordx2 v[52:53], v[54:55], off
	global_store_dwordx2 v[60:61], v[50:51], off offset:32
	s_and_b64 vcc, exec, s[6:7]
	v_or_b32_e32 v50, 32, v74
	s_cbranch_vccnz .LBB0_749
	s_waitcnt vmcnt(14)
	v_pk_mul_f32 v[60:61], v[44:45], v[178:179]
	v_pk_mul_f32 v[62:63], v[42:43], v[176:177]
	v_pk_mul_f32 v[178:179], v[48:49], v[178:179]
	v_pk_mul_f32 v[176:177], v[46:47], v[176:177]
	v_pk_fma_f32 v[48:49], v[48:49], v[182:183], v[60:61] neg_lo:[0,0,1] neg_hi:[0,0,1]
	v_pk_fma_f32 v[46:47], v[46:47], v[180:181], v[62:63] neg_lo:[0,0,1] neg_hi:[0,0,1]
	v_pk_fma_f32 v[44:45], v[44:45], v[182:183], v[178:179]
	v_pk_fma_f32 v[42:43], v[42:43], v[180:181], v[176:177]
.LBB0_749:
	v_mov_b64_e32 v[52:53], s[16:17]
	v_mad_i64_i32 v[50:51], s[38:39], v50, s45, v[52:53]
	v_lshl_add_u64 v[50:51], v[50:51], 0, v[0:1]
	v_lshl_add_u64 v[50:51], s[36:37], 1, v[50:51]
	v_cvt_pk_bf16_f32 v46, v46, v47
	v_cvt_pk_bf16_f32 v47, v48, v49
	v_cvt_pk_bf16_f32 v42, v42, v43
	v_cvt_pk_bf16_f32 v43, v44, v45
	v_add_co_u32_e32 v44, vcc, 0x1000, v50
	v_lshl_add_u64 v[52:53], v[50:51], 0, s[84:85]
	s_nop 0
	v_addc_co_u32_e32 v45, vcc, 0, v51, vcc
	global_store_dwordx2 v[44:45], v[46:47], off
	global_store_dwordx2 v[52:53], v[42:43], off offset:32
	s_and_b64 vcc, exec, s[6:7]
	v_or_b32_e32 v42, 48, v74
	s_cbranch_vccnz .LBB0_751
	s_waitcnt vmcnt(14)
	v_pk_mul_f32 v[52:53], v[36:37], v[186:187]
	v_pk_mul_f32 v[54:55], v[34:35], v[184:185]
	v_pk_mul_f32 v[186:187], v[40:41], v[186:187]
	v_pk_mul_f32 v[184:185], v[38:39], v[184:185]
	v_pk_fma_f32 v[40:41], v[40:41], v[190:191], v[52:53] neg_lo:[0,0,1] neg_hi:[0,0,1]
	v_pk_fma_f32 v[38:39], v[38:39], v[188:189], v[54:55] neg_lo:[0,0,1] neg_hi:[0,0,1]
	v_pk_fma_f32 v[36:37], v[36:37], v[190:191], v[186:187]
	v_pk_fma_f32 v[34:35], v[34:35], v[188:189], v[184:185]
.LBB0_751:
	v_mov_b64_e32 v[44:45], s[16:17]
	v_mad_i64_i32 v[42:43], s[38:39], v42, s45, v[44:45]
	v_lshl_add_u64 v[42:43], v[42:43], 0, v[0:1]
	v_lshl_add_u64 v[42:43], s[36:37], 1, v[42:43]
	v_cvt_pk_bf16_f32 v38, v38, v39
	v_cvt_pk_bf16_f32 v39, v40, v41
	v_cvt_pk_bf16_f32 v34, v34, v35
	v_cvt_pk_bf16_f32 v35, v36, v37
	v_add_co_u32_e32 v36, vcc, 0x1000, v42
	v_lshl_add_u64 v[44:45], v[42:43], 0, s[84:85]
	s_nop 0
	v_addc_co_u32_e32 v37, vcc, 0, v43, vcc
	global_store_dwordx2 v[36:37], v[38:39], off
	global_store_dwordx2 v[44:45], v[34:35], off offset:32
	s_and_b64 vcc, exec, s[6:7]
	v_add_u32_e32 v34, 0x80, v74
	s_cbranch_vccnz .LBB0_753
	s_waitcnt vmcnt(14)
	v_pk_mul_f32 v[44:45], v[28:29], v[194:195]
	v_pk_mul_f32 v[46:47], v[26:27], v[192:193]
	v_pk_mul_f32 v[194:195], v[32:33], v[194:195]
	v_pk_mul_f32 v[192:193], v[30:31], v[192:193]
	v_pk_fma_f32 v[32:33], v[32:33], v[198:199], v[44:45] neg_lo:[0,0,1] neg_hi:[0,0,1]
	v_pk_fma_f32 v[30:31], v[30:31], v[196:197], v[46:47] neg_lo:[0,0,1] neg_hi:[0,0,1]
	v_pk_fma_f32 v[28:29], v[28:29], v[198:199], v[194:195]
	v_pk_fma_f32 v[26:27], v[26:27], v[196:197], v[192:193]
; __device__ __forceinline__ unsigned cvt_pk_bf16(float lo, float hi) { unsigned r; asm volatile("v_cvt_pk_bf16_f32 %0, %1, %2" : "=v"(r) : "v"(lo), "v"(hi)); return r; }
;     __device__ __forceinline__ void operator()(const f32x4 (&acc)[2][2][4][2], const Unit& u, int wr, int wc, int fr_in, int fq_in) const {
;     ...
;             for (int ai = 0; ai < 2; ++ai)
; #pragma unroll
;                 for (int m = 0; m < 4; ++m) {
;                     const int r = row0 + ai * HALF + m * 16;
;                     f32x4 x1 = acc[ai][bj][m][0] * qs, x2 = acc[ai][bj][m][1] * qs;
;                     if (isrope) {
;                         const int s = r % LP;
;                         const f32x4 cs = *(const f32x4*)(rope + (size_t)s * 32 + 4 * fq), sn = *(const f32x4*)(rope + (size_t)s * 32 + 16 + 4 * fq);
;                         const f32x4 o1 = x1 * cs - x2 * sn, o2 = x2 * cs + x1 * sn; x1 = o1; x2 = o2;
;                     }
;                     bf16_t* p = U + (size_t)r * DIN + 2048 + cg0 + 4 * fq;
;                     u32x2 w1, w2; w1.x = cvt_pk_bf16(x1[0], x1[1]); w1.y = cvt_pk_bf16(x1[2], x1[3]); w2.x = cvt_pk_bf16(x2[0], x2[1]); w2.y = cvt_pk_bf16(x2[2], x2[3]);
;                     *(u32x2*)p = w1; *(u32x2*)(p + 16) = w2;
.LBB0_753:
	v_mov_b64_e32 v[36:37], s[16:17]
	v_mad_i64_i32 v[34:35], s[38:39], v34, s45, v[36:37]
	v_lshl_add_u64 v[34:35], v[34:35], 0, v[0:1]
	v_lshl_add_u64 v[34:35], s[36:37], 1, v[34:35]
	v_cvt_pk_bf16_f32 v30, v30, v31
	v_cvt_pk_bf16_f32 v31, v32, v33
	v_cvt_pk_bf16_f32 v26, v26, v27
	v_cvt_pk_bf16_f32 v27, v28, v29
	v_add_co_u32_e32 v28, vcc, 0x1000, v34
	v_lshl_add_u64 v[36:37], v[34:35], 0, s[84:85]
	s_nop 0
	v_addc_co_u32_e32 v29, vcc, 0, v35, vcc
	global_store_dwordx2 v[28:29], v[30:31], off
	global_store_dwordx2 v[36:37], v[26:27], off offset:32
	s_and_b64 vcc, exec, s[6:7]
	v_add_u32_e32 v26, 0x90, v74
	s_cbranch_vccnz .LBB0_755
	s_waitcnt vmcnt(14)
	v_pk_mul_f32 v[36:37], v[20:21], v[202:203]
	v_pk_mul_f32 v[38:39], v[18:19], v[200:201]
	v_pk_mul_f32 v[202:203], v[24:25], v[202:203]
	v_pk_mul_f32 v[200:201], v[22:23], v[200:201]
	v_pk_fma_f32 v[24:25], v[24:25], v[206:207], v[36:37] neg_lo:[0,0,1] neg_hi:[0,0,1]
	v_pk_fma_f32 v[22:23], v[22:23], v[204:205], v[38:39] neg_lo:[0,0,1] neg_hi:[0,0,1]
	v_pk_fma_f32 v[20:21], v[20:21], v[206:207], v[202:203]
	v_pk_fma_f32 v[18:19], v[18:19], v[204:205], v[200:201]
.LBB0_755:
	v_mov_b64_e32 v[28:29], s[16:17]
	v_mad_i64_i32 v[26:27], s[38:39], v26, s45, v[28:29]
	v_lshl_add_u64 v[26:27], v[26:27], 0, v[0:1]
	v_lshl_add_u64 v[26:27], s[36:37], 1, v[26:27]
	v_cvt_pk_bf16_f32 v22, v22, v23
	v_cvt_pk_bf16_f32 v23, v24, v25
	v_cvt_pk_bf16_f32 v18, v18, v19
	v_cvt_pk_bf16_f32 v19, v20, v21
	v_add_co_u32_e32 v20, vcc, 0x1000, v26
	v_lshl_add_u64 v[28:29], v[26:27], 0, s[84:85]
	s_nop 0
	v_addc_co_u32_e32 v21, vcc, 0, v27, vcc
	global_store_dwordx2 v[20:21], v[22:23], off
	global_store_dwordx2 v[28:29], v[18:19], off offset:32
	s_and_b64 vcc, exec, s[6:7]
	v_add_u32_e32 v18, 0xa0, v74
	s_cbranch_vccnz .LBB0_757
	s_waitcnt vmcnt(14)
	v_pk_mul_f32 v[28:29], v[12:13], v[210:211]
	v_pk_mul_f32 v[30:31], v[10:11], v[208:209]
	v_pk_mul_f32 v[210:211], v[16:17], v[210:211]
	v_pk_mul_f32 v[208:209], v[14:15], v[208:209]
	v_pk_fma_f32 v[16:17], v[16:17], v[222:223], v[28:29] neg_lo:[0,0,1] neg_hi:[0,0,1]
	v_pk_fma_f32 v[14:15], v[14:15], v[220:221], v[30:31] neg_lo:[0,0,1] neg_hi:[0,0,1]
	v_pk_fma_f32 v[12:13], v[12:13], v[222:223], v[210:211]
	v_pk_fma_f32 v[10:11], v[10:11], v[220:221], v[208:209]
.LBB0_757:
	v_mov_b64_e32 v[20:21], s[16:17]
	v_mad_i64_i32 v[18:19], s[38:39], v18, s45, v[20:21]
	v_lshl_add_u64 v[18:19], v[18:19], 0, v[0:1]
	v_lshl_add_u64 v[18:19], s[36:37], 1, v[18:19]
	v_cvt_pk_bf16_f32 v14, v14, v15
	v_cvt_pk_bf16_f32 v15, v16, v17
	v_cvt_pk_bf16_f32 v10, v10, v11
	v_cvt_pk_bf16_f32 v11, v12, v13
	v_add_co_u32_e32 v12, vcc, 0x1000, v18
	v_lshl_add_u64 v[20:21], v[18:19], 0, s[84:85]
	s_nop 0
	v_addc_co_u32_e32 v13, vcc, 0, v19, vcc
	global_store_dwordx2 v[12:13], v[14:15], off
	global_store_dwordx2 v[20:21], v[10:11], off offset:32
	s_and_b64 vcc, exec, s[6:7]
	v_add_u32_e32 v10, 0xb0, v74
	s_cbranch_vccnz .LBB0_759
	s_waitcnt vmcnt(14)
	v_pk_mul_f32 v[20:21], v[4:5], v[226:227]
	v_pk_mul_f32 v[22:23], v[2:3], v[224:225]
	v_pk_mul_f32 v[226:227], v[8:9], v[226:227]
	v_pk_mul_f32 v[224:225], v[6:7], v[224:225]
	v_pk_fma_f32 v[8:9], v[8:9], v[230:231], v[20:21] neg_lo:[0,0,1] neg_hi:[0,0,1]
	v_pk_fma_f32 v[6:7], v[6:7], v[228:229], v[22:23] neg_lo:[0,0,1] neg_hi:[0,0,1]
	v_pk_fma_f32 v[4:5], v[4:5], v[230:231], v[226:227]
	v_pk_fma_f32 v[2:3], v[2:3], v[228:229], v[224:225]
.LBB0_759:
	v_mov_b64_e32 v[12:13], s[16:17]
	v_mad_i64_i32 v[10:11], s[6:7], v10, s45, v[12:13]
	v_lshl_add_u64 v[10:11], v[10:11], 0, v[0:1]
	v_lshl_add_u64 v[10:11], s[36:37], 1, v[10:11]
	v_cvt_pk_bf16_f32 v6, v6, v7
	v_cvt_pk_bf16_f32 v7, v8, v9
	v_cvt_pk_bf16_f32 v2, v2, v3
	v_cvt_pk_bf16_f32 v3, v4, v5
	v_add_co_u32_e32 v4, vcc, 0x1000, v10
	v_lshl_add_u64 v[12:13], v[10:11], 0, s[84:85]
	s_nop 0
	v_addc_co_u32_e32 v5, vcc, 0, v11, vcc
	global_store_dwordx2 v[4:5], v[6:7], off
	global_store_dwordx2 v[12:13], v[2:3], off offset:32
	s_and_b64 vcc, exec, s[4:5]
	s_mov_b64 s[4:5], -1
	s_cbranch_vccnz .LBB0_706
